# v55 plus sgemm_phase K loop staged through wave-private LDS by LDS-DMA (16-row x 64-B pieces, two k-steps in flight)
# speedup vs baseline: 1.0136x; 1.0044x over previous
.LBB0_505:
	s_ashr_i32 s11, s3, 31
	s_lshr_b32 s11, s11, 27
	s_add_i32 s11, s3, s11
	s_ashr_i32 s20, s11, 5
	s_lshl_b32 s11, s20, 6
	s_lshl_b32 s21, s20, 10
	s_lshl_b32 s20, s3, 5
	s_sub_i32 s20, s20, s21
	s_ashr_i32 s39, s20, 8
	s_mul_i32 s40, s39, s73
	s_ashr_i32 s41, s40, 31
	v_add_u32_e32 v2, s11, v61
	s_lshl_b64 s[40:41], s[40:41], 1
	v_ashrrev_i32_e32 v3, 31, v2
	v_mov_b64_e32 v[0:1], s[40:41]
	v_mad_u64_u32 v[0:1], s[40:41], s4, v2, v[0:1]
	v_mul_lo_u32 v3, s4, v3
	v_mul_lo_u32 v2, s5, v2
	v_add3_u32 v1, v2, v1, v3
	v_lshl_add_u64 v[48:49], v[36:37], 0, v[0:1]
	v_lshl_add_u64 v[50:51], v[38:39], 0, v[0:1]
	v_lshl_add_u64 v[52:53], v[40:41], 0, v[0:1]
	v_lshl_add_u64 v[54:55], v[42:43], 0, v[0:1]
	v_subrev_u32_e32 v0, s21, v62
	v_ashrrev_i32_e32 v1, 31, v0
	v_mad_u64_u32 v[56:57], s[40:41], s8, v0, v[44:45]
	v_mul_lo_u32 v1, s8, v1
	v_mul_lo_u32 v2, s9, v0
	v_mad_u64_u32 v[58:59], s[40:41], s8, v0, v[46:47]
	v_mov_b32_e32 v0, 0
	v_add3_u32 v57, v2, v57, v1
	v_add3_u32 v59, v2, v59, v1
	s_mov_b32 s21, 0
	v_mov_b32_e32 v1, v0
	v_mov_b32_e32 v2, v0
	v_mov_b32_e32 v3, v0
	v_mov_b32_e32 v4, v0
	v_mov_b32_e32 v5, v0
	v_mov_b32_e32 v6, v0
	v_mov_b32_e32 v7, v0
	v_mov_b32_e32 v8, v0
	v_mov_b32_e32 v9, v0
	v_mov_b32_e32 v10, v0
	v_mov_b32_e32 v11, v0
	v_mov_b32_e32 v12, v0
	v_mov_b32_e32 v13, v0
	v_mov_b32_e32 v14, v0
	v_mov_b32_e32 v15, v0
	v_mov_b32_e32 v16, v0
	v_mov_b32_e32 v17, v0
	v_mov_b32_e32 v18, v0
	v_mov_b32_e32 v19, v0
	v_mov_b32_e32 v20, v0
	v_mov_b32_e32 v21, v0
	v_mov_b32_e32 v22, v0
	v_mov_b32_e32 v23, v0
	v_mov_b32_e32 v24, v0
	v_mov_b32_e32 v25, v0
	v_mov_b32_e32 v26, v0
	v_mov_b32_e32 v27, v0
	v_mov_b32_e32 v28, v0
	v_mov_b32_e32 v29, v0
	v_mov_b32_e32 v30, v0
	v_mov_b32_e32 v31, v0
	s_and_b32 vcc_lo, s38, 0x7f
	s_cbranch_scc1 .Lsgp_orig
	v_and_b32_e32 v188, 63, v176
	v_lshrrev_b32_e32 v189, 2, v188
	v_and_b32_e32 v190, 15, v188
	v_sub_u32_e32 v189, v189, v190
	v_and_b32_e32 v191, 3, v188
	v_lshrrev_b32_e32 v192, 4, v188
	v_sub_u32_e32 v191, v191, v192
	v_lshlrev_b32_e32 v191, 4, v191
	v_mul_lo_u32 v193, v189, s4
	v_add_u32_e32 v194, v193, v191
	v_ashrrev_i32_e32 v195, 31, v194
	v_mul_lo_u32 v193, v189, s8
	v_add_u32_e32 v196, v193, v191
	v_ashrrev_i32_e32 v197, 31, v196
	v_lshl_add_u64 v[114:115], v[56:57], 0, v[34:35]
	v_lshl_add_u64 v[114:115], v[114:115], 0, v[196:197]
	v_lshl_add_u64 v[116:117], v[58:59], 0, v[34:35]
	v_lshl_add_u64 v[116:117], v[116:117], 0, v[196:197]
	v_lshl_add_u64 v[118:119], v[48:49], 0, v[34:35]
	v_lshl_add_u64 v[118:119], v[118:119], 0, v[194:195]
	v_lshl_add_u64 v[120:121], v[50:51], 0, v[34:35]
	v_lshl_add_u64 v[120:121], v[120:121], 0, v[194:195]
	v_lshl_add_u64 v[122:123], v[52:53], 0, v[34:35]
	v_lshl_add_u64 v[122:123], v[122:123], 0, v[194:195]
	v_lshl_add_u64 v[124:125], v[54:55], 0, v[34:35]
	v_lshl_add_u64 v[124:125], v[124:125], 0, v[194:195]
	v_lshlrev_b32_e32 v189, 6, v190
	v_lshl_add_u32 v198, v192, 4, v189
	v_lshrrev_b32_e32 v188, 6, v176
	s_nop 1
	v_readfirstlane_b32 s100, v188
	s_nop 3
	s_lshl_b32 s100, s100, 14
	s_add_i32 s100, s100, 0x800
	s_nop 0
	v_add_u32_e32 v198, s100, v198
	s_add_i32 m0, s100, 0
	s_nop 0
	global_load_lds_dwordx4 v[114:115], off
	s_add_i32 m0, s100, 1024
	s_nop 0
	global_load_lds_dwordx4 v[116:117], off
	s_add_i32 m0, s100, 2048
	s_nop 0
	global_load_lds_dwordx4 v[118:119], off
	s_add_i32 m0, s100, 3072
	s_nop 0
	global_load_lds_dwordx4 v[120:121], off
	s_add_i32 m0, s100, 4096
	s_nop 0
	global_load_lds_dwordx4 v[122:123], off
	s_add_i32 m0, s100, 5120
	s_nop 0
	global_load_lds_dwordx4 v[124:125], off
	s_add_i32 m0, s100, 6080
	s_nop 0
	global_load_lds_dwordx4 v[114:115], off offset:64
	s_add_i32 m0, s100, 7104
	s_nop 0
	global_load_lds_dwordx4 v[116:117], off offset:64
	s_add_i32 m0, s100, 8128
	s_nop 0
	global_load_lds_dwordx4 v[118:119], off offset:64
	s_add_i32 m0, s100, 9152
	s_nop 0
	global_load_lds_dwordx4 v[120:121], off offset:64
	s_add_i32 m0, s100, 10176
	s_nop 0
	global_load_lds_dwordx4 v[122:123], off offset:64
	s_add_i32 m0, s100, 11200
	s_nop 0
	global_load_lds_dwordx4 v[124:125], off offset:64
	s_movk_i32 s21, 0x40
.Lsgp_loop:
	s_cmp_ge_u32 s21, s38
	s_cbranch_scc1 .Lsgp_final
	s_waitcnt vmcnt(6)
	ds_read_b128 v[66:69], v198
	ds_read_b128 v[70:73], v198 offset:1024
	ds_read_b128 v[74:77], v198 offset:2048
	ds_read_b128 v[78:81], v198 offset:3072
	ds_read_b128 v[82:85], v198 offset:4096
	ds_read_b128 v[86:89], v198 offset:5120
	s_waitcnt lgkmcnt(0)
	v_lshl_add_u64 v[114:115], 64, 1, v[114:115]
	v_lshl_add_u64 v[116:117], 64, 1, v[116:117]
	v_lshl_add_u64 v[118:119], 64, 1, v[118:119]
	v_lshl_add_u64 v[120:121], 64, 1, v[120:121]
	v_lshl_add_u64 v[122:123], 64, 1, v[122:123]
	v_lshl_add_u64 v[124:125], 64, 1, v[124:125]
	s_add_i32 m0, s100, 0
	s_nop 0
	global_load_lds_dwordx4 v[114:115], off
	s_add_i32 m0, s100, 1024
	s_nop 0
	global_load_lds_dwordx4 v[116:117], off
	s_add_i32 m0, s100, 2048
	s_nop 0
	global_load_lds_dwordx4 v[118:119], off
	s_add_i32 m0, s100, 3072
	s_nop 0
	global_load_lds_dwordx4 v[120:121], off
	s_add_i32 m0, s100, 4096
	s_nop 0
	global_load_lds_dwordx4 v[122:123], off
	s_add_i32 m0, s100, 5120
	s_nop 0
	global_load_lds_dwordx4 v[124:125], off
	v_mfma_f32_16x16x32_bf16 v[28:31], v[66:69], v[74:77], v[28:31]
	v_mfma_f32_16x16x32_bf16 v[24:27], v[70:73], v[74:77], v[24:27]
	v_mfma_f32_16x16x32_bf16 v[20:23], v[66:69], v[78:81], v[20:23]
	v_mfma_f32_16x16x32_bf16 v[16:19], v[70:73], v[78:81], v[16:19]
	v_mfma_f32_16x16x32_bf16 v[12:15], v[66:69], v[82:85], v[12:15]
	v_mfma_f32_16x16x32_bf16 v[8:11], v[70:73], v[82:85], v[8:11]
	v_mfma_f32_16x16x32_bf16 v[4:7], v[66:69], v[86:89], v[4:7]
	v_mfma_f32_16x16x32_bf16 v[0:3], v[70:73], v[86:89], v[0:3]
	s_waitcnt vmcnt(6)
	ds_read_b128 v[90:93], v198 offset:6144
	ds_read_b128 v[94:97], v198 offset:7168
	ds_read_b128 v[98:101], v198 offset:8192
	ds_read_b128 v[102:105], v198 offset:9216
	ds_read_b128 v[106:109], v198 offset:10240
	ds_read_b128 v[110:113], v198 offset:11264
	s_waitcnt lgkmcnt(0)
	s_add_i32 m0, s100, 6080
	s_nop 0
	global_load_lds_dwordx4 v[114:115], off offset:64
	s_add_i32 m0, s100, 7104
	s_nop 0
	global_load_lds_dwordx4 v[116:117], off offset:64
	s_add_i32 m0, s100, 8128
	s_nop 0
	global_load_lds_dwordx4 v[118:119], off offset:64
	s_add_i32 m0, s100, 9152
	s_nop 0
	global_load_lds_dwordx4 v[120:121], off offset:64
	s_add_i32 m0, s100, 10176
	s_nop 0
	global_load_lds_dwordx4 v[122:123], off offset:64
	s_add_i32 m0, s100, 11200
	s_nop 0
	global_load_lds_dwordx4 v[124:125], off offset:64
	v_mfma_f32_16x16x32_bf16 v[28:31], v[90:93], v[98:101], v[28:31]
	v_mfma_f32_16x16x32_bf16 v[24:27], v[94:97], v[98:101], v[24:27]
	v_mfma_f32_16x16x32_bf16 v[20:23], v[90:93], v[102:105], v[20:23]
	v_mfma_f32_16x16x32_bf16 v[16:19], v[94:97], v[102:105], v[16:19]
	v_mfma_f32_16x16x32_bf16 v[12:15], v[90:93], v[106:109], v[12:15]
	v_mfma_f32_16x16x32_bf16 v[8:11], v[94:97], v[106:109], v[8:11]
	v_mfma_f32_16x16x32_bf16 v[4:7], v[90:93], v[110:113], v[4:7]
	v_mfma_f32_16x16x32_bf16 v[0:3], v[94:97], v[110:113], v[0:3]
	s_addk_i32 s21, 0x40
	s_branch .Lsgp_loop
.Lsgp_final:
	s_waitcnt vmcnt(6)
	ds_read_b128 v[66:69], v198
	ds_read_b128 v[70:73], v198 offset:1024
	ds_read_b128 v[74:77], v198 offset:2048
	ds_read_b128 v[78:81], v198 offset:3072
	ds_read_b128 v[82:85], v198 offset:4096
	ds_read_b128 v[86:89], v198 offset:5120
	s_waitcnt lgkmcnt(0)
	v_mfma_f32_16x16x32_bf16 v[28:31], v[66:69], v[74:77], v[28:31]
	v_mfma_f32_16x16x32_bf16 v[24:27], v[70:73], v[74:77], v[24:27]
	v_mfma_f32_16x16x32_bf16 v[20:23], v[66:69], v[78:81], v[20:23]
	v_mfma_f32_16x16x32_bf16 v[16:19], v[70:73], v[78:81], v[16:19]
	v_mfma_f32_16x16x32_bf16 v[12:15], v[66:69], v[82:85], v[12:15]
	v_mfma_f32_16x16x32_bf16 v[8:11], v[70:73], v[82:85], v[8:11]
	v_mfma_f32_16x16x32_bf16 v[4:7], v[66:69], v[86:89], v[4:7]
	v_mfma_f32_16x16x32_bf16 v[0:3], v[70:73], v[86:89], v[0:3]
	s_waitcnt vmcnt(0)
	ds_read_b128 v[90:93], v198 offset:6144
	ds_read_b128 v[94:97], v198 offset:7168
	ds_read_b128 v[98:101], v198 offset:8192
	ds_read_b128 v[102:105], v198 offset:9216
	ds_read_b128 v[106:109], v198 offset:10240
	ds_read_b128 v[110:113], v198 offset:11264
	s_waitcnt lgkmcnt(0)
	v_mfma_f32_16x16x32_bf16 v[28:31], v[90:93], v[98:101], v[28:31]
	v_mfma_f32_16x16x32_bf16 v[24:27], v[94:97], v[98:101], v[24:27]
	v_mfma_f32_16x16x32_bf16 v[20:23], v[90:93], v[102:105], v[20:23]
	v_mfma_f32_16x16x32_bf16 v[16:19], v[94:97], v[102:105], v[16:19]
	v_mfma_f32_16x16x32_bf16 v[12:15], v[90:93], v[106:109], v[12:15]
	v_mfma_f32_16x16x32_bf16 v[8:11], v[94:97], v[106:109], v[8:11]
	v_mfma_f32_16x16x32_bf16 v[4:7], v[90:93], v[110:113], v[4:7]
	v_mfma_f32_16x16x32_bf16 v[0:3], v[94:97], v[110:113], v[0:3]
	s_nop 1
	s_branch .Lsgp_done

.Lsgp_done:
	s_barrier
	ds_write_b128 v63, v[28:31]
	ds_write_b128 v63, v[24:27] offset:64
	ds_write_b128 v63, v[20:23] offset:2304
	ds_write_b128 v63, v[16:19] offset:2368
	ds_write_b128 v63, v[12:15] offset:4608
	ds_write_b128 v63, v[8:11] offset:4672
	ds_write_b128 v64, v[4:7]
	ds_write_b128 v64, v[0:3] offset:64
	s_waitcnt lgkmcnt(0)
	s_barrier
	ds_read_b128 v[0:3], v65
	ds_read_b128 v[4:7], v65 offset:9216
	ds_read_b128 v[8:11], v65 offset:18432
	s_ashr_i32 s21, s20, 31
	s_and_b64 vcc, exec, s[0:1]
	s_waitcnt lgkmcnt(2)
	v_pk_add_f32 v[2:3], v[2:3], 0 op_sel_hi:[1,0]
	v_pk_add_f32 v[12:13], v[0:1], 0 op_sel_hi:[1,0]
	s_waitcnt lgkmcnt(1)
	v_pk_add_f32 v[6:7], v[2:3], v[6:7]
	ds_read_b128 v[0:3], v65 offset:27648
	v_pk_add_f32 v[12:13], v[12:13], v[4:5]
	s_waitcnt lgkmcnt(1)
	v_pk_add_f32 v[10:11], v[6:7], v[10:11]
	ds_read_b128 v[4:7], v65 offset:36864
	v_pk_add_f32 v[8:9], v[12:13], v[8:9]
	s_waitcnt lgkmcnt(1)
	v_pk_add_f32 v[10:11], v[10:11], v[2:3]
	v_pk_add_f32 v[12:13], v[8:9], v[0:1]
	ds_read_b128 v[0:3], v65 offset:46080
	s_waitcnt lgkmcnt(1)
	v_pk_add_f32 v[14:15], v[10:11], v[6:7]
	ds_read_b128 v[6:9], v65 offset:55296
	v_pk_add_f32 v[4:5], v[12:13], v[4:5]
	ds_read_b128 v[10:13], v65 offset:64512
	s_waitcnt lgkmcnt(2)
	v_pk_add_f32 v[2:3], v[14:15], v[2:3]
	v_pk_add_f32 v[0:1], v[4:5], v[0:1]
	s_waitcnt lgkmcnt(1)
	v_pk_add_f32 v[2:3], v[2:3], v[8:9]
	v_pk_add_f32 v[4:5], v[0:1], v[6:7]
	s_waitcnt lgkmcnt(0)
	v_pk_add_f32 v[0:1], v[2:3], v[12:13]
	v_pk_add_f32 v[2:3], v[4:5], v[10:11]
	s_cbranch_vccz .LBB0_504
	v_lshl_add_u64 v[4:5], s[20:21], 2, v[32:33]
	global_load_dwordx4 v[4:7], v[4:5], off
	s_waitcnt vmcnt(0)
	v_pk_mul_f32 v[0:1], v[0:1], v[6:7]
	v_pk_mul_f32 v[2:3], v[2:3], v[4:5]
	s_branch .LBB0_504
